# hand-written gated-delta scan loop: 12-deep LDS fragment ring, counted lgkmcnt, stores in MFMA gaps, compact DMA issue
# speedup vs baseline: 1.2224x; 1.2224x over previous
.LBB0_582:
	s_mov_b32 s3, 0
	s_lshl_b64 s[54:55], s[2:3], 19
	s_add_u32 s7, s34, s54
	s_addc_u32 s16, s35, s55
	s_lshl_b32 s6, s2, 20
	s_mul_i32 s71, s2, 0x1c0000
	s_lshl_b32 s4, s2, 5
	s_and_b32 s0, s6, 0x1c00000
	s_mul_hi_u32 s70, s2, 0x1c0000
	s_mov_b32 s5, s3
	s_add_u32 s17, s30, s71
	s_addc_u32 s18, s31, s70
	s_lshl_b64 s[4:5], s[4:5], 2
	s_add_u32 s4, s48, s4
	s_addc_u32 s5, s49, s5
	s_lshl_b32 s6, s44, 10
	v_lshlrev_b32_e32 v48, 2, v56
	v_mov_b32_e32 v49, 0
	s_add_i32 s72, s6, 0xffff2000
	v_lshl_add_u64 v[0:1], s[4:5], 0, v[48:49]
	s_add_u32 s5, s7, s72
	s_addc_u32 s20, s16, 0
	s_ashr_i32 s65, s6, 31
	s_add_u32 s21, s17, s6
	s_addc_u32 s22, s18, s65
	s_add_i32 s56, s6, 0x2000
	s_add_i32 s23, s6, 0
	s_ashr_i32 s64, s56, 31
	s_add_u32 s26, s17, s56
	s_addc_u32 s27, s18, s64
	s_add_i32 s74, s6, 0xffff4000
	s_add_u32 s36, s7, s74
	s_addc_u32 s37, s16, 0
	s_add_i32 s66, s6, 0x4000
	s_add_i32 s38, s23, 0x2000
	s_ashr_i32 s67, s66, 31
	s_add_u32 s39, s17, s66
	s_addc_u32 s42, s18, s67
	s_add_i32 s78, s6, 0xffff6000
	s_add_u32 s43, s7, s78
	s_addc_u32 s50, s16, 0
	s_add_i32 s68, s6, 0x6000
	s_add_i32 s51, s23, 0x4000
	s_ashr_i32 s69, s68, 31
	s_add_u32 s57, s17, s68
	s_addc_u32 s89, s18, s69
	s_add_i32 s80, s6, 0xffff8000
	s_mov_b32 s4, 0x1d0000
	s_add_u32 s91, s7, s80
	v_add_co_u32_e32 v0, vcc, s4, v0
	s_addc_u32 s96, s16, 0
	s_add_i32 s73, s6, 0x8000
	v_addc_co_u32_e32 v1, vcc, 0, v1, vcc
	s_add_i32 s97, s23, 0x6000
	s_ashr_i32 s75, s73, 31
	s_add_u32 vcc_lo, s17, s73
	s_addc_u32 vcc_hi, s18, s75
	s_add_i32 s82, s6, 0xffffa000
	s_add_u32 s76, s7, s82
	s_mov_b32 s90, s44
	s_addc_u32 s44, s16, 0
	s_add_i32 s79, s6, 0xa000
	s_add_i32 s45, s23, 0x8000
	s_ashr_i32 s81, s79, 31
	s_add_u32 s87, s17, s79
	s_addc_u32 s46, s18, s81
	s_add_i32 s84, s6, 0xffffc000
	s_add_u32 s47, s7, s84
	s_addc_u32 s86, s16, 0
	s_add_i32 s83, s6, 0xc000
	v_writelane_b32 v233, s52, 36
	s_add_i32 s8, s23, 0xa000
	s_ashr_i32 s85, s83, 31
	v_writelane_b32 v233, s53, 37
	s_add_u32 s9, s17, s83
	v_writelane_b32 v233, s0, 38
	s_addc_u32 s0, s18, s85
	s_add_i32 s88, s6, 0xffffe000
	s_add_u32 s1, s7, s88
	s_addc_u32 s52, s16, 0
	s_add_i32 s53, s23, 0xc000
	s_add_u32 s58, s7, s6
	s_addc_u32 s59, s16, 0
	s_add_i32 s14, s23, 0xe000
	s_add_i32 s4, s6, 0x10000
	s_add_u32 s60, s7, s56
	s_addc_u32 s61, s16, 0
	s_add_i32 s15, s23, 0x10000
	s_add_u32 s12, s7, 0x4000
	s_addc_u32 s13, s16, 0
	s_add_u32 s7, s17, 0xe000
	s_addc_u32 s24, s18, 0
	s_add_u32 s25, s7, s6
	s_addc_u32 s62, s24, s65
	s_add_u32 s92, s12, s72
	s_addc_u32 s63, s13, 0
	s_cmpk_lt_u32 s33, 0xe00
	s_cselect_b64 s[16:17], -1, 0
	s_and_b64 s[18:19], s[16:17], exec
	s_cselect_b32 s19, s22, s20
	s_cselect_b32 s18, s21, s5
	s_cselect_b32 s63, s62, s63
	s_cselect_b32 s62, s25, s92
	s_add_i32 s5, 0, 0x12000
	s_add_i32 s25, s5, s6
	s_add_u32 s22, s7, s56
	s_mov_b32 m0, s23
	s_addc_u32 s23, s24, s64
	s_add_u32 s92, s12, s74
	s_addc_u32 s93, s13, 0
	v_lshlrev_b32_e32 v48, 4, v218
	s_cmpk_lt_u32 s33, 0xc00
	global_load_lds_dwordx4 v48, s[18:19]
	s_cselect_b64 s[18:19], -1, 0
	s_and_b64 s[20:21], s[18:19], exec
	s_cselect_b32 s21, s27, s37
	s_cselect_b32 s20, s26, s36
	s_cselect_b32 s92, s22, s92
	s_cselect_b32 s93, s23, s93
	s_add_i32 s10, s5, s56
	s_add_u32 s11, s7, s66
	s_addc_u32 s26, s24, s67
	s_add_u32 s27, s12, s78
	s_addc_u32 s36, s13, 0
	s_mov_b32 m0, s38
	s_cmpk_lt_u32 s33, 0xa00
	global_load_lds_dwordx4 v48, s[20:21]
	s_cselect_b64 s[20:21], -1, 0
	s_and_b64 s[22:23], s[20:21], exec
	s_cselect_b32 s23, s42, s50
	s_cselect_b32 s22, s39, s43
	s_cselect_b32 s95, s26, s36
	s_cselect_b32 s94, s11, s27
	s_add_i32 s11, s5, s66
	s_add_u32 s36, s7, s68
	s_addc_u32 s37, s24, s69
	s_add_u32 s38, s12, s80
	s_addc_u32 s39, s13, 0
	s_mov_b32 m0, s51
	s_cmpk_lt_u32 s33, 0x800
	global_load_lds_dwordx4 v48, s[22:23]
	s_cselect_b64 s[22:23], -1, 0
	s_and_b64 s[26:27], s[22:23], exec
	s_cselect_b32 s27, s89, s96
	s_cselect_b32 s26, s57, s91
	s_mov_b32 m0, s97
	s_cselect_b32 s96, s36, s38
	s_cselect_b32 s97, s37, s39
	s_add_i32 s89, s5, s68
	s_add_u32 s38, s7, s73
	s_addc_u32 s39, s24, s75
	s_add_u32 s42, s12, s82
	s_addc_u32 s43, s13, 0
	s_cmpk_lt_u32 s33, 0x600
	global_load_lds_dwordx4 v48, s[26:27]
	s_cselect_b64 s[26:27], -1, 0
	s_and_b64 s[36:37], s[26:27], exec
	s_cselect_b32 s37, vcc_hi, s44
	s_cselect_b32 s36, vcc_lo, s76
	s_cselect_b32 vcc_hi, s39, s43
	s_cselect_b32 vcc_lo, s38, s42
	s_add_i32 s91, s5, s73
	s_add_u32 s42, s7, s79
	s_addc_u32 s43, s24, s81
	s_add_u32 s44, s12, s84
	s_mov_b32 m0, s45
	s_addc_u32 s45, s13, 0
	s_cmpk_lt_u32 s33, 0x400
	global_load_lds_dwordx4 v48, s[36:37]
	s_cselect_b64 s[36:37], -1, 0
	s_and_b64 s[38:39], s[36:37], exec
	s_cselect_b32 s39, s46, s86
	s_cselect_b32 s38, s87, s47
	s_mov_b32 m0, s8
	s_cselect_b32 s50, s42, s44
	s_cselect_b32 s51, s43, s45
	s_add_i32 s8, s5, s79
	s_add_u32 s44, s7, s83
	s_addc_u32 s24, s24, s85
	s_add_u32 s45, s12, s88
	s_addc_u32 s46, s13, 0
	s_cmpk_lt_u32 s33, 0x200
	global_load_lds_dwordx4 v48, s[38:39]
	s_cselect_b64 s[38:39], -1, 0
	s_and_b64 s[42:43], s[38:39], exec
	s_cselect_b32 s43, s0, s52
	s_cselect_b32 s42, s9, s1
	s_mov_b32 m0, s53
	global_load_dword v57, v[0:1], off
	s_mov_b32 s7, s3
	global_load_lds_dwordx4 v48, s[42:43]
	s_mov_b32 m0, s14
	s_mov_b32 s57, s3
	global_load_lds_dwordx4 v48, s[58:59]
	s_mov_b32 m0, s15
	v_or_b32_e32 v0, s54, v48
	global_load_lds_dwordx4 v48, s[60:61]
	s_mov_b32 m0, s25
	v_mov_b32_e32 v1, s55
	global_load_lds_dwordx4 v48, s[62:63]
	s_mov_b32 m0, s10
	v_lshl_add_u64 v[2:3], v[0:1], 0, s[6:7]
	global_load_lds_dwordx4 v48, s[92:93]
	s_mov_b32 m0, s11
	v_lshl_add_u64 v[0:1], v[0:1], 0, s[56:57]
	global_load_lds_dwordx4 v48, s[94:95]
	s_mov_b32 m0, s89
	v_readlane_b32 s7, v233, 38
	global_load_lds_dwordx4 v48, s[96:97]
	s_mov_b32 m0, s91
	s_mov_b64 s[42:43], 0x4000
	global_load_lds_dwordx4 v48, vcc
	s_mov_b32 m0, s8
	v_mov_b32_e32 v4, v49
	global_load_lds_dwordx4 v48, s[50:51]
	s_cselect_b32 s51, s24, s46
	s_cselect_b32 s50, s44, s45
	s_add_i32 m0, s5, s83
	s_mov_b32 s44, s90
	global_load_lds_dwordx4 v48, s[50:51]
	s_add_u32 s50, s12, s6
	s_addc_u32 s51, s13, 0
	s_add_i32 m0, s25, 0xe000
	v_mov_b32_e32 v5, v49
	global_load_lds_dwordx4 v48, s[50:51]
	s_add_u32 s50, s12, s56
	s_addc_u32 s51, s13, 0
	s_add_i32 m0, s5, s4
	s_lshl_b32 s5, s90, 11
	global_load_lds_dwordx4 v48, s[50:51]
	s_add_u32 s0, s71, s6
	s_addc_u32 s1, s70, s65
	s_add_u32 s0, s30, s0
	s_addc_u32 s1, s31, s1
	s_add_u32 s58, s0, 0x1c000
	s_addc_u32 s59, s1, 0
	s_add_u32 s0, s71, s56
	s_addc_u32 s1, s70, s64
	s_add_u32 s0, s30, s0
	s_addc_u32 s1, s31, s1
	s_add_u32 s60, s0, 0x1c000
	s_addc_u32 s61, s1, 0
	s_add_u32 s0, s71, s66
	s_addc_u32 s1, s70, s67
	s_add_u32 s0, s30, s0
	s_addc_u32 s1, s31, s1
	s_add_u32 s62, s0, 0x1c000
	s_addc_u32 s63, s1, 0
	s_add_u32 s0, s71, s68
	s_addc_u32 s1, s70, s69
	s_add_u32 s0, s30, s0
	s_addc_u32 s1, s31, s1
	s_add_u32 s64, s0, 0x1c000
	s_addc_u32 s65, s1, 0
	s_add_u32 s0, s71, s73
	s_addc_u32 s1, s70, s75
	s_add_u32 s0, s30, s0
	s_addc_u32 s1, s31, s1
	s_add_u32 s66, s0, 0x1c000
	s_addc_u32 s67, s1, 0
	s_add_u32 s0, s71, s79
	s_addc_u32 s1, s70, s81
	s_add_u32 s0, s30, s0
	s_addc_u32 s1, s31, s1
	s_add_u32 s68, s0, 0x1c000
	s_addc_u32 s69, s1, 0
	s_add_u32 s0, s71, s83
	s_addc_u32 s1, s70, s85
	s_add_u32 s0, s30, s0
	s_addc_u32 s1, s31, s1
	s_add_u32 s70, s0, 0x1c000
	s_addc_u32 s71, s1, 0
	s_add_u32 s0, s54, s72
	s_addc_u32 s1, s55, 0
	s_add_u32 s72, s0, 0x1c08000
	s_addc_u32 s73, s1, 0
	s_add_u32 s0, s54, s74
	s_addc_u32 s1, s55, 0
	s_add_u32 s74, s0, 0x1c08000
	s_addc_u32 s75, s1, 0
	s_add_u32 s0, s54, s78
	s_addc_u32 s1, s55, 0
	s_add_u32 s78, s0, 0x1c08000
	s_addc_u32 s79, s1, 0
	s_add_u32 s0, s54, s80
	s_addc_u32 s1, s55, 0
	s_add_u32 s80, s0, 0x1c08000
	s_addc_u32 s81, s1, 0
	s_add_u32 s0, s54, s82
	s_addc_u32 s1, s55, 0
	s_add_u32 s82, s0, 0x1c08000
	s_addc_u32 s83, s1, 0
	s_add_u32 s0, s54, s84
	s_addc_u32 s1, s55, 0
	s_add_u32 s84, s0, 0x1c08000
	s_addc_u32 s85, s1, 0
	s_add_u32 s0, s54, s88
	s_addc_u32 s1, s55, 0
	s_add_u32 s88, s0, 0x1c08000
	s_addc_u32 s89, s1, 0
	s_and_b32 s0, s2, 3
	s_lshl_b32 s0, s0, 9
	s_and_b32 s1, s33, 0xffffffc0
	s_add_u32 s0, s1, s0
	s_mov_b64 s[50:51], 0x1c08000
	s_addc_u32 s1, 0, 0
	v_lshl_add_u64 v[50:51], v[2:3], 0, s[50:51]
	v_lshl_add_u64 v[52:53], v[0:1], 0, s[50:51]
	v_lshlrev_b32_e32 v0, 9, v188
	s_add_u32 s50, s0, s7
	s_waitcnt vmcnt(0)
	v_and_b32_e32 v0, 0x6000, v0
	v_mov_b32_e32 v1, v49
	s_addc_u32 s51, s1, 0
	v_lshl_add_u64 v[54:55], s[50:51], 0, v[0:1]
	v_lshl_or_b32 v54, v165, 2, v54
	s_mov_b64 s[54:55], 0
	v_mov_b32_e32 v0, v49
	v_mov_b32_e32 v2, v49
	v_mov_b32_e32 v3, v49
	v_mov_b32_e32 v6, v49
	v_mov_b32_e32 v7, v49
	v_mov_b32_e32 v8, v49
	v_mov_b32_e32 v9, v49
	v_mov_b32_e32 v10, v49
	v_mov_b32_e32 v11, v49
	v_mov_b32_e32 v12, v49
	v_mov_b32_e32 v13, v49
	v_mov_b32_e32 v14, v49
	v_mov_b32_e32 v15, v49
	v_mov_b32_e32 v16, v49
	v_mov_b32_e32 v17, v49
	v_mov_b32_e32 v18, v49
	v_mov_b32_e32 v19, v49
	v_mov_b32_e32 v20, v49
	v_mov_b32_e32 v21, v49
	v_mov_b32_e32 v22, v49
	v_mov_b32_e32 v23, v49
	v_mov_b32_e32 v28, v49
	v_mov_b32_e32 v29, v49
	v_mov_b32_e32 v30, v49
	v_mov_b32_e32 v31, v49
	v_mov_b32_e32 v24, v49
	v_mov_b32_e32 v25, v49
	v_mov_b32_e32 v26, v49
	v_mov_b32_e32 v27, v49
	s_waitcnt vmcnt(0) lgkmcnt(0)
	s_barrier
	s_lshl_b32 s6, s44, 10
	s_mul_i32 s1, s2, 0x1c0000
	s_add_u32 s1, s1, s6
	s_add_u32 s1, s1, 0x1c000
	s_add_u32 s10, s30, s1
	s_addc_u32 s11, s31, 0
	s_lshl_b32 s1, s2, 19
	s_add_u32 s1, s1, s6
	s_add_u32 s1, s1, 0x8000
	s_add_u32 s12, s34, s1
	s_addc_u32 s13, s35, 0
	s_lshr_b32 s1, s2, 2
	s_lshl_b32 s1, s1, 22
	s_add_u32 s1, s1, 0xcc00000
	s_add_u32 s14, s48, s1
	s_addc_u32 s15, s49, 0
	s_and_b32 s0, s2, 3
	s_lshl_b32 s0, s0, 9
	s_lshl_b32 s1, s44, 6
	s_add_i32 s0, s0, s1
	v_lshlrev_b32_e32 v190, 9, v188
	v_and_b32_e32 v190, 0x6000, v190
	v_lshl_or_b32 v190, v165, 2, v190
	v_add_u32_e32 v190, s0, v190
	v_add_u32_e32 v191, 0x1000, v190
	v_add_u32_e32 v192, 0x8000, v190
	v_add_u32_e32 v193, 0x9000, v190
	v_add_u32_e32 v194, 0x10000, v190
	v_add_u32_e32 v195, 0x11000, v190
	v_add_u32_e32 v196, 0x18000, v190
	v_add_u32_e32 v197, 0x19000, v190
	v_add_u32_e32 v181, 0x2000, v48
	v_add_u32_e32 v182, 0x4000, v48
	v_add_u32_e32 v183, 0x6000, v48
	v_add_u32_e32 v184, 0x8000, v48
	v_add_u32_e32 v185, 0xa000, v48
	v_add_u32_e32 v186, 0xc000, v48
	v_mov_b32_e32 v93, v48
	v_add_u32_e32 v94, s5, v161
	s_mov_b32 s3, 0
	s_mov_b32 s8, 0x12000
	s_mov_b32 s9, 0
	ds_read_b128 v[120:123], v93 offset:6144
	ds_read_b128 v[124:127], v93 offset:7168
	ds_read_b128 v[128:131], v93 offset:8192
	ds_read_b128 v[132:135], v93 offset:9216
	ds_read_b128 v[136:139], v93 offset:10240
	ds_read_b128 v[140:143], v93 offset:11264
	ds_read_b128 v[96:99], v93
	ds_read_b128 v[100:103], v93 offset:1024
	ds_read_b128 v[104:107], v93 offset:2048
	ds_read_b128 v[108:111], v93 offset:3072
	ds_read_b128 v[112:115], v93 offset:4096
	ds_read_b128 v[116:119], v93 offset:5120
	ds_read2st64_b64 v[172:175], v94 offset0:112 offset1:113
	ds_read2st64_b64 v[176:179], v94 offset0:114 offset1:115
.Lscan_loop:
	v_readlane_b32 s56, v57, s3
	v_cvt_pk_bf16_f32 v144, v0, v1
	v_cvt_pk_bf16_f32 v145, v2, v3
	v_cvt_pk_bf16_f32 v146, v4, v5
	v_cvt_pk_bf16_f32 v147, v6, v7
	v_cvt_pk_bf16_f32 v148, v8, v9
	v_cvt_pk_bf16_f32 v149, v10, v11
	v_cvt_pk_bf16_f32 v150, v12, v13
	v_cvt_pk_bf16_f32 v151, v14, v15
	s_waitcnt lgkmcnt(7)
	v_mfma_f32_16x16x32_bf16 v[64:67], v[96:99], v[144:147], 0
	ds_read_b128 v[96:99], v93 offset:12288
	v_cvt_pk_bf16_f32 v152, v16, v17
	v_cvt_pk_bf16_f32 v153, v18, v19
	v_cvt_pk_bf16_f32 v154, v20, v21
	v_cvt_pk_bf16_f32 v155, v22, v23
	s_waitcnt lgkmcnt(7)
	v_mfma_f32_16x16x32_bf16 v[64:67], v[100:103], v[148:151], v[64:67]
	ds_read_b128 v[100:103], v93 offset:13312
	v_cvt_pk_bf16_f32 v156, v28, v29
	v_cvt_pk_bf16_f32 v157, v30, v31
	v_cvt_pk_bf16_f32 v158, v24, v25
	v_cvt_pk_bf16_f32 v159, v26, v27
	s_waitcnt lgkmcnt(7)
	v_mfma_f32_16x16x32_bf16 v[64:67], v[104:107], v[152:155], v[64:67]
	ds_read_b128 v[104:107], v93 offset:14336
	v_mul_f32_e32 v0, s56, v0
	v_mul_f32_e32 v1, s56, v1
	s_waitcnt lgkmcnt(7)
	v_mfma_f32_16x16x32_bf16 v[64:67], v[108:111], v[156:159], v[64:67]
	ds_read_b128 v[108:111], v93 offset:15360
	v_mul_f32_e32 v2, s56, v2
	v_mul_f32_e32 v3, s56, v3
	s_waitcnt lgkmcnt(7)
	v_mfma_f32_16x16x32_bf16 v[68:71], v[112:115], v[144:147], 0
	ds_read_b128 v[112:115], v93 offset:16384
	v_mul_f32_e32 v4, s56, v4
	v_mul_f32_e32 v5, s56, v5
	s_waitcnt lgkmcnt(7)
	v_mfma_f32_16x16x32_bf16 v[68:71], v[116:119], v[148:151], v[68:71]
	ds_read_b128 v[116:119], v93 offset:17408
	v_mul_f32_e32 v6, s56, v6
	v_mul_f32_e32 v7, s56, v7
	v_mfma_f32_16x16x32_bf16 v[68:71], v[120:123], v[152:155], v[68:71]
	ds_read_b128 v[120:123], v93 offset:18432
	v_mul_f32_e32 v8, s56, v8
	v_mul_f32_e32 v9, s56, v9
	v_mfma_f32_16x16x32_bf16 v[68:71], v[124:127], v[156:159], v[68:71]
	ds_read_b128 v[124:127], v93 offset:19456
	v_mul_f32_e32 v10, s56, v10
	v_mul_f32_e32 v11, s56, v11
	v_mfma_f32_16x16x32_bf16 v[72:75], v[128:131], v[144:147], 0
	ds_read_b128 v[128:131], v93 offset:20480
	v_mul_f32_e32 v12, s56, v12
	v_mul_f32_e32 v13, s56, v13
	v_mfma_f32_16x16x32_bf16 v[72:75], v[132:135], v[148:151], v[72:75]
	ds_read_b128 v[132:135], v93 offset:21504
	v_mul_f32_e32 v14, s56, v14
	v_mul_f32_e32 v15, s56, v15
	v_mfma_f32_16x16x32_bf16 v[72:75], v[136:139], v[152:155], v[72:75]
	ds_read_b128 v[136:139], v93 offset:22528
	v_mul_f32_e32 v16, s56, v16
	v_mul_f32_e32 v17, s56, v17
	v_mfma_f32_16x16x32_bf16 v[72:75], v[140:143], v[156:159], v[72:75]
	ds_read_b128 v[140:143], v93 offset:23552
	v_mul_f32_e32 v18, s56, v18
	v_mul_f32_e32 v19, s56, v19
	s_waitcnt lgkmcnt(11)
	v_mfma_f32_16x16x32_bf16 v[76:79], v[96:99], v[144:147], 0
	ds_read_b128 v[96:99], v93 offset:24576
	v_lshlrev_b32_e32 v88, 16, v172
	v_and_b32_e32 v89, 0xffff0000, v172
	v_sub_f32_e32 v64, v88, v64
	v_sub_f32_e32 v65, v89, v65
	s_waitcnt lgkmcnt(11)
	v_mfma_f32_16x16x32_bf16 v[76:79], v[100:103], v[148:151], v[76:79]
	ds_read_b128 v[100:103], v93 offset:25600
	v_lshlrev_b32_e32 v88, 16, v173
	v_and_b32_e32 v89, 0xffff0000, v173
	v_sub_f32_e32 v66, v88, v66
	v_sub_f32_e32 v67, v89, v67
	s_waitcnt lgkmcnt(11)
	v_mfma_f32_16x16x32_bf16 v[76:79], v[104:107], v[152:155], v[76:79]
	ds_read_b128 v[104:107], v93 offset:26624
	v_lshlrev_b32_e32 v88, 16, v174
	v_and_b32_e32 v89, 0xffff0000, v174
	v_sub_f32_e32 v68, v88, v68
	v_sub_f32_e32 v69, v89, v69
	s_waitcnt lgkmcnt(11)
	v_mfma_f32_16x16x32_bf16 v[76:79], v[108:111], v[156:159], v[76:79]
	ds_read_b128 v[108:111], v93 offset:27648
	v_lshlrev_b32_e32 v88, 16, v175
	v_and_b32_e32 v89, 0xffff0000, v175
	v_sub_f32_e32 v70, v88, v70
	v_sub_f32_e32 v71, v89, v71
	s_waitcnt lgkmcnt(11)
	v_mfma_f32_16x16x32_bf16 v[32:35], v[112:115], v[144:147], 0
	ds_read_b128 v[112:115], v93 offset:28672
	v_cvt_pk_bf16_f32 v80, v64, v65
	v_cvt_pk_bf16_f32 v81, v66, v67
	v_cvt_pk_bf16_f32 v82, v68, v69
	v_cvt_pk_bf16_f32 v83, v70, v71
	s_waitcnt lgkmcnt(11)
	v_mfma_f32_16x16x32_bf16 v[32:35], v[116:119], v[148:151], v[32:35]
	ds_read_b128 v[116:119], v93 offset:29696
	v_lshlrev_b32_e32 v88, 16, v176
	v_and_b32_e32 v89, 0xffff0000, v176
	v_sub_f32_e32 v72, v88, v72
	v_sub_f32_e32 v73, v89, v73
	s_waitcnt lgkmcnt(11)
	v_mfma_f32_16x16x32_bf16 v[32:35], v[120:123], v[152:155], v[32:35]
	ds_read_b128 v[120:123], v93 offset:30720
	v_lshlrev_b32_e32 v88, 16, v177
	v_and_b32_e32 v89, 0xffff0000, v177
	v_sub_f32_e32 v74, v88, v74
	v_sub_f32_e32 v75, v89, v75
	s_waitcnt lgkmcnt(11)
	v_mfma_f32_16x16x32_bf16 v[32:35], v[124:127], v[156:159], v[32:35]
	ds_read_b128 v[124:127], v93 offset:31744
	v_lshlrev_b32_e32 v88, 16, v178
	v_and_b32_e32 v89, 0xffff0000, v178
	v_sub_f32_e32 v76, v88, v76
	v_sub_f32_e32 v77, v89, v77
	s_waitcnt lgkmcnt(11)
	v_mfma_f32_16x16x32_bf16 v[36:39], v[128:131], v[144:147], 0
	ds_read_b128 v[128:131], v93 offset:32768
	v_lshlrev_b32_e32 v88, 16, v179
	v_and_b32_e32 v89, 0xffff0000, v179
	v_sub_f32_e32 v78, v88, v78
	v_sub_f32_e32 v79, v89, v79
	s_waitcnt lgkmcnt(11)
	v_mfma_f32_16x16x32_bf16 v[36:39], v[132:135], v[148:151], v[36:39]
	ds_read_b128 v[132:135], v93 offset:34816
	v_cvt_pk_bf16_f32 v84, v72, v73
	v_cvt_pk_bf16_f32 v85, v74, v75
	v_cvt_pk_bf16_f32 v86, v76, v77
	v_cvt_pk_bf16_f32 v87, v78, v79
	s_waitcnt lgkmcnt(11)
	v_mfma_f32_16x16x32_bf16 v[36:39], v[136:139], v[152:155], v[36:39]
	ds_read_b128 v[136:139], v93 offset:36864
	v_mul_f32_e32 v20, s56, v20
	s_waitcnt lgkmcnt(11)
	v_mfma_f32_16x16x32_bf16 v[36:39], v[140:143], v[156:159], v[36:39]
	ds_read_b128 v[140:143], v93 offset:37888
	v_mul_f32_e32 v21, s56, v21
	s_waitcnt lgkmcnt(11)
	v_mfma_f32_16x16x32_bf16 v[40:43], v[96:99], v[144:147], 0
	ds_read_b128 v[96:99], v93 offset:38912
	v_mul_f32_e32 v22, s56, v22
	s_waitcnt lgkmcnt(11)
	v_mfma_f32_16x16x32_bf16 v[40:43], v[100:103], v[148:151], v[40:43]
	ds_read_b128 v[100:103], v93 offset:39936
	v_mul_f32_e32 v23, s56, v23
	s_waitcnt lgkmcnt(11)
	v_mfma_f32_16x16x32_bf16 v[40:43], v[104:107], v[152:155], v[40:43]
	ds_read_b128 v[104:107], v93 offset:40960
	v_mul_f32_e32 v24, s56, v24
	s_waitcnt lgkmcnt(11)
	v_mfma_f32_16x16x32_bf16 v[40:43], v[108:111], v[156:159], v[40:43]
	ds_read_b128 v[108:111], v93 offset:41984
	v_mul_f32_e32 v25, s56, v25
	s_waitcnt lgkmcnt(11)
	v_mfma_f32_16x16x32_bf16 v[44:47], v[112:115], v[144:147], 0
	ds_read_b128 v[112:115], v93 offset:43008
	v_mul_f32_e32 v26, s56, v26
	s_waitcnt lgkmcnt(11)
	v_mfma_f32_16x16x32_bf16 v[44:47], v[116:119], v[148:151], v[44:47]
	ds_read_b128 v[116:119], v93 offset:44032
	v_mul_f32_e32 v27, s56, v27
	s_waitcnt lgkmcnt(11)
	v_mfma_f32_16x16x32_bf16 v[44:47], v[120:123], v[152:155], v[44:47]
	ds_read_b128 v[120:123], v93 offset:45056
	v_mul_f32_e32 v28, s56, v28
	s_waitcnt lgkmcnt(11)
	v_mfma_f32_16x16x32_bf16 v[44:47], v[124:127], v[156:159], v[44:47]
	ds_read_b128 v[124:127], v93 offset:46080
	v_mul_f32_e32 v29, s56, v29
	s_waitcnt lgkmcnt(11)
	v_mfma_f32_16x16x32_bf16 v[32:35], v[128:131], v[80:83], v[32:35]
	ds_read_b128 v[128:131], v93 offset:47104
	v_mul_f32_e32 v30, s56, v30
	s_waitcnt lgkmcnt(11)
	v_mfma_f32_16x16x32_bf16 v[36:39], v[132:135], v[80:83], v[36:39]
	ds_read_b128 v[132:135], v93 offset:48128
	v_mul_f32_e32 v31, s56, v31
	s_waitcnt lgkmcnt(11)
	v_mfma_f32_16x16x32_bf16 v[40:43], v[136:139], v[80:83], v[40:43]
	ds_read_b128 v[136:139], v93 offset:49152
	s_waitcnt lgkmcnt(11)
	v_mfma_f32_16x16x32_bf16 v[40:43], v[140:143], v[84:87], v[40:43]
	ds_read_b128 v[140:143], v93 offset:50176
	s_waitcnt lgkmcnt(11)
	v_mfma_f32_16x16x32_bf16 v[44:47], v[96:99], v[80:83], v[44:47]
	ds_read_b128 v[96:99], v93 offset:51200
	s_waitcnt lgkmcnt(11)
	v_mfma_f32_16x16x32_bf16 v[44:47], v[100:103], v[84:87], v[44:47]
	ds_read_b128 v[100:103], v93 offset:52224
	s_waitcnt lgkmcnt(11)
	v_mfma_f32_16x16x32_bf16 v[0:3], v[104:107], v[80:83], v[0:3]
	ds_read_b128 v[104:107], v93 offset:53248
	s_waitcnt lgkmcnt(11)
	v_mfma_f32_16x16x32_bf16 v[0:3], v[108:111], v[84:87], v[0:3]
	ds_read_b128 v[108:111], v93 offset:54272
	global_store_dword v190, v32, s[14:15]
	global_store_dword v190, v33, s[14:15] offset:2048
	s_waitcnt lgkmcnt(11)
	v_mfma_f32_16x16x32_bf16 v[4:7], v[112:115], v[80:83], v[4:7]
	ds_read_b128 v[112:115], v93 offset:55296
	global_store_dword v191, v34, s[14:15]
	global_store_dword v191, v35, s[14:15] offset:2048
	s_waitcnt lgkmcnt(11)
	v_mfma_f32_16x16x32_bf16 v[4:7], v[116:119], v[84:87], v[4:7]
	ds_read_b128 v[116:119], v93 offset:56320
	global_store_dword v192, v36, s[14:15]
	global_store_dword v192, v37, s[14:15] offset:2048
	s_waitcnt lgkmcnt(11)
	v_mfma_f32_16x16x32_bf16 v[8:11], v[120:123], v[80:83], v[8:11]
	global_store_dword v193, v38, s[14:15]
	global_store_dword v193, v39, s[14:15] offset:2048
	v_add_u32_e32 v93, s8, v93
	v_add_u32_e32 v94, s8, v94
	s_sub_i32 s8, 0, s8
	s_waitcnt lgkmcnt(10)
	v_mfma_f32_16x16x32_bf16 v[8:11], v[124:127], v[84:87], v[8:11]
	global_store_dword v194, v40, s[14:15]
	global_store_dword v194, v41, s[14:15] offset:2048
	s_waitcnt lgkmcnt(9)
	v_mfma_f32_16x16x32_bf16 v[12:15], v[128:131], v[80:83], v[12:15]
	global_store_dword v195, v42, s[14:15]
	global_store_dword v195, v43, s[14:15] offset:2048
	s_waitcnt lgkmcnt(8)
	v_mfma_f32_16x16x32_bf16 v[12:15], v[132:135], v[84:87], v[12:15]
	global_store_dword v196, v44, s[14:15]
	global_store_dword v196, v45, s[14:15] offset:2048
	s_waitcnt lgkmcnt(7)
	v_mfma_f32_16x16x32_bf16 v[16:19], v[136:139], v[80:83], v[16:19]
	global_store_dword v197, v46, s[14:15]
	global_store_dword v197, v47, s[14:15] offset:2048
	s_waitcnt lgkmcnt(6)
	v_mfma_f32_16x16x32_bf16 v[16:19], v[140:143], v[84:87], v[16:19]
	s_waitcnt lgkmcnt(0)
	s_waitcnt vmcnt(16)
	s_barrier
	ds_read_b128 v[120:123], v93 offset:6144
	ds_read_b128 v[124:127], v93 offset:7168
	ds_read_b128 v[128:131], v93 offset:8192
	ds_read_b128 v[132:135], v93 offset:9216
	ds_read_b128 v[136:139], v93 offset:10240
	ds_read_b128 v[140:143], v93 offset:11264
	v_mfma_f32_16x16x32_bf16 v[20:23], v[96:99], v[80:83], v[20:23]
	ds_read_b128 v[96:99], v93
	v_mfma_f32_16x16x32_bf16 v[20:23], v[100:103], v[84:87], v[20:23]
	ds_read_b128 v[100:103], v93 offset:1024
	v_mfma_f32_16x16x32_bf16 v[28:31], v[104:107], v[80:83], v[28:31]
	ds_read_b128 v[104:107], v93 offset:2048
	v_mfma_f32_16x16x32_bf16 v[28:31], v[108:111], v[84:87], v[28:31]
	ds_read_b128 v[108:111], v93 offset:3072
	v_mfma_f32_16x16x32_bf16 v[24:27], v[112:115], v[80:83], v[24:27]
	ds_read_b128 v[112:115], v93 offset:4096
	v_mfma_f32_16x16x32_bf16 v[24:27], v[116:119], v[84:87], v[24:27]
	ds_read_b128 v[116:119], v93 offset:5120
	ds_read2st64_b64 v[172:175], v94 offset0:112 offset1:113
	ds_read2st64_b64 v[176:179], v94 offset0:114 offset1:115
	s_cmp_gt_u32 s3, 29
	s_cbranch_scc1 .Lscan_nodma
	s_add_i32 s0, s9, s6
	s_add_i32 m0, s0, 0x0
	s_nop 0
	global_load_lds_dwordx4 v48, s[10:11]
	s_add_i32 m0, s0, 0x2000
	s_nop 0
	global_load_lds_dwordx4 v181, s[10:11]
	s_add_i32 m0, s0, 0x4000
	s_nop 0
	global_load_lds_dwordx4 v182, s[10:11]
	s_add_i32 m0, s0, 0x6000
	s_nop 0
	global_load_lds_dwordx4 v183, s[10:11]
	s_add_i32 m0, s0, 0x8000
	s_nop 0
	global_load_lds_dwordx4 v184, s[10:11]
	s_add_i32 m0, s0, 0xa000
	s_nop 0
	global_load_lds_dwordx4 v185, s[10:11]
	s_add_i32 m0, s0, 0xc000
	s_nop 0
	global_load_lds_dwordx4 v186, s[10:11]
	s_add_i32 m0, s0, 0xe000
	s_nop 0
	global_load_lds_dwordx4 v48, s[12:13]
	s_add_i32 m0, s0, 0x10000
	s_nop 0
	global_load_lds_dwordx4 v181, s[12:13]
	s_add_u32 s10, s10, 0xe000
	s_addc_u32 s11, s11, 0
	s_add_u32 s12, s12, 0x4000
	s_addc_u32 s13, s13, 0
.Lscan_nodma:
	s_xor_b32 s9, s9, 0x12000
	s_add_u32 s14, s14, 0x20000
	s_addc_u32 s15, s15, 0
	s_add_i32 s3, s3, 1
	s_cmp_lt_u32 s3, 32
	s_cbranch_scc1 .Lscan_loop
